# final RMSNorm pipelined (2 rows/iteration, prefetch) with bounds guard on the second row (robust to any workgroup count)
# speedup vs baseline: 1.0137x; 1.0137x over previous
.LBB0_1097:
	global_load_dwordx4 v[24:27], v[2:3], off
	global_load_dwordx4 v[28:31], v[2:3], off offset:16
	global_load_dwordx4 v[32:35], v[2:3], off offset:2048
	global_load_dwordx4 v[36:39], v[2:3], off offset:2064
	s_add_u32 s10, s72, s7
	s_addc_u32 s11, s73, s8
	global_load_dwordx2 v[18:19], v1, s[10:11]
	v_lshl_add_u64 v[16:17], s[72:73], 0, v[4:5]
	v_add_co_u32_e32 v16, vcc, s9, v16
	s_nop 1
	v_addc_co_u32_e32 v17, vcc, 0, v17, vcc
	global_load_dwordx4 v[8:11], v[16:17], off
	global_load_dwordx4 v[40:43], v[16:17], off offset:1024
	s_add_i32 s6, s6, s12
	s_mov_b32 s15, 0
	s_cmpk_gt_i32 s6, 0x7fff
	s_cbranch_scc1 .Lfn_nb0
	s_mov_b32 s15, 1
	s_add_u32 s10, s10, s0
	s_addc_u32 s11, s11, s1
	global_load_dwordx2 v[64:65], v1, s[10:11]
	v_lshl_add_u64 v[106:107], v[16:17], 0, s[2:3]
	global_load_dwordx4 v[66:69], v[106:107], off
	global_load_dwordx4 v[70:73], v[106:107], off offset:1024
.Lfn_nb0:
	s_add_u32 s7, s7, s0
	s_addc_u32 s8, s8, s1
	s_add_u32 s7, s7, s0
	s_addc_u32 s8, s8, s1
	v_lshl_add_u64 v[4:5], v[4:5], 0, s[2:3]
	v_lshl_add_u64 v[4:5], v[4:5], 0, s[2:3]
	s_add_i32 s6, s6, s12
	s_waitcnt vmcnt(0)
	s_branch .Lfn_body

.Lfn_body:
	v_mov_b64_e32 v[44:45], v[18:19]
	v_mov_b64_e32 v[46:47], v[8:9]
	v_mov_b64_e32 v[48:49], v[10:11]
	v_mov_b64_e32 v[50:51], v[40:41]
	v_mov_b64_e32 v[52:53], v[42:43]
	v_mov_b64_e32 v[74:75], v[64:65]
	v_mov_b64_e32 v[76:77], v[66:67]
	v_mov_b64_e32 v[78:79], v[68:69]
	v_mov_b64_e32 v[80:81], v[70:71]
	v_mov_b64_e32 v[82:83], v[72:73]
	s_mov_b32 s16, s15
	s_cmpk_gt_i32 s6, 0x7fff
	s_cselect_b32 s14, 1, 0
	s_cbranch_scc1 .Lfn_nopf
	s_add_u32 s10, s72, s7
	s_addc_u32 s11, s73, s8
	global_load_dwordx2 v[18:19], v1, s[10:11]
	v_lshl_add_u64 v[16:17], s[72:73], 0, v[4:5]
	v_add_co_u32_e32 v16, vcc, s9, v16
	s_nop 1
	v_addc_co_u32_e32 v17, vcc, 0, v17, vcc
	global_load_dwordx4 v[8:11], v[16:17], off
	global_load_dwordx4 v[40:43], v[16:17], off offset:1024
	s_add_i32 s6, s6, s12
	s_mov_b32 s15, 0
	s_cmpk_gt_i32 s6, 0x7fff
	s_cbranch_scc1 .Lfn_nb1
	s_mov_b32 s15, 1
	s_add_u32 s10, s10, s0
	s_addc_u32 s11, s11, s1
	global_load_dwordx2 v[64:65], v1, s[10:11]
	v_lshl_add_u64 v[106:107], v[16:17], 0, s[2:3]
	global_load_dwordx4 v[66:69], v[106:107], off
	global_load_dwordx4 v[70:73], v[106:107], off offset:1024
.Lfn_nb1:
	s_add_u32 s7, s7, s0
	s_addc_u32 s8, s8, s1
	s_add_u32 s7, s7, s0
	s_addc_u32 s8, s8, s1
	v_lshl_add_u64 v[4:5], v[4:5], 0, s[2:3]
	v_lshl_add_u64 v[4:5], v[4:5], 0, s[2:3]
	s_add_i32 s6, s6, s12
.Lfn_nopf:
	v_lshl_add_u64 v[108:109], v[6:7], 0, s[4:5]
	v_ffbh_u32_e32 v102, v45
	v_min_u32_e32 v102, 32, v102
	v_lshlrev_b64 v[104:105], v102, v[44:45]
	v_min_u32_e32 v104, 1, v104
	v_or_b32_e32 v104, v105, v104
	v_cvt_f32_u32_e32 v104, v104
	v_sub_u32_e32 v102, 32, v102
	v_ldexp_f32 v104, v104, v102
	v_mul_f32_e32 v104, 0x37800000, v104
	v_fmamk_f32 v104, v104, 0x3a800000, v0
	v_rsq_f32_e32 v54, v104
	v_lshlrev_b32_e32 v12, 16, v46
	v_and_b32_e32 v13, 0xffff0000, v46
	v_lshlrev_b32_e32 v14, 16, v47
	v_and_b32_e32 v15, 0xffff0000, v47
	v_pk_mul_f32 v[12:13], v[54:55], v[12:13] op_sel_hi:[0,1]
	v_pk_mul_f32 v[14:15], v[54:55], v[14:15] op_sel_hi:[0,1]
	v_pk_mul_f32 v[12:13], v[24:25], v[12:13]
	v_pk_mul_f32 v[14:15], v[26:27], v[14:15]
	global_store_dwordx4 v[6:7], v[12:15], off offset:-2064 nt
	v_lshlrev_b32_e32 v20, 16, v48
	v_and_b32_e32 v21, 0xffff0000, v48
	v_lshlrev_b32_e32 v22, 16, v49
	v_and_b32_e32 v23, 0xffff0000, v49
	v_pk_mul_f32 v[20:21], v[54:55], v[20:21] op_sel_hi:[0,1]
	v_pk_mul_f32 v[22:23], v[54:55], v[22:23] op_sel_hi:[0,1]
	v_pk_mul_f32 v[20:21], v[28:29], v[20:21]
	v_pk_mul_f32 v[22:23], v[30:31], v[22:23]
	global_store_dwordx4 v[6:7], v[20:23], off offset:-2048 nt
	v_lshlrev_b32_e32 v56, 16, v50
	v_and_b32_e32 v57, 0xffff0000, v50
	v_lshlrev_b32_e32 v58, 16, v51
	v_and_b32_e32 v59, 0xffff0000, v51
	v_pk_mul_f32 v[56:57], v[54:55], v[56:57] op_sel_hi:[0,1]
	v_pk_mul_f32 v[58:59], v[54:55], v[58:59] op_sel_hi:[0,1]
	v_pk_mul_f32 v[56:57], v[32:33], v[56:57]
	v_pk_mul_f32 v[58:59], v[34:35], v[58:59]
	global_store_dwordx4 v[6:7], v[56:59], off offset:-16 nt
	v_lshlrev_b32_e32 v60, 16, v52
	v_and_b32_e32 v61, 0xffff0000, v52
	v_lshlrev_b32_e32 v62, 16, v53
	v_and_b32_e32 v63, 0xffff0000, v53
	v_pk_mul_f32 v[60:61], v[54:55], v[60:61] op_sel_hi:[0,1]
	v_pk_mul_f32 v[62:63], v[54:55], v[62:63] op_sel_hi:[0,1]
	v_pk_mul_f32 v[60:61], v[36:37], v[60:61]
	v_pk_mul_f32 v[62:63], v[38:39], v[62:63]
	global_store_dwordx4 v[6:7], v[60:63], off nt
	s_cmp_eq_u32 s16, 0
	s_cbranch_scc1 .Lfn_skipB
	v_ffbh_u32_e32 v102, v75
	v_min_u32_e32 v102, 32, v102
	v_lshlrev_b64 v[104:105], v102, v[74:75]
	v_min_u32_e32 v104, 1, v104
	v_or_b32_e32 v104, v105, v104
	v_cvt_f32_u32_e32 v104, v104
	v_sub_u32_e32 v102, 32, v102
	v_ldexp_f32 v104, v104, v102
	v_mul_f32_e32 v104, 0x37800000, v104
	v_fmamk_f32 v104, v104, 0x3a800000, v0
	v_rsq_f32_e32 v100, v104
	v_lshlrev_b32_e32 v84, 16, v76
	v_and_b32_e32 v85, 0xffff0000, v76
	v_lshlrev_b32_e32 v86, 16, v77
	v_and_b32_e32 v87, 0xffff0000, v77
	v_pk_mul_f32 v[84:85], v[100:101], v[84:85] op_sel_hi:[0,1]
	v_pk_mul_f32 v[86:87], v[100:101], v[86:87] op_sel_hi:[0,1]
	v_pk_mul_f32 v[84:85], v[24:25], v[84:85]
	v_pk_mul_f32 v[86:87], v[26:27], v[86:87]
	global_store_dwordx4 v[108:109], v[84:87], off offset:-2064 nt
	v_lshlrev_b32_e32 v88, 16, v78
	v_and_b32_e32 v89, 0xffff0000, v78
	v_lshlrev_b32_e32 v90, 16, v79
	v_and_b32_e32 v91, 0xffff0000, v79
	v_pk_mul_f32 v[88:89], v[100:101], v[88:89] op_sel_hi:[0,1]
	v_pk_mul_f32 v[90:91], v[100:101], v[90:91] op_sel_hi:[0,1]
	v_pk_mul_f32 v[88:89], v[28:29], v[88:89]
	v_pk_mul_f32 v[90:91], v[30:31], v[90:91]
	global_store_dwordx4 v[108:109], v[88:91], off offset:-2048 nt
	v_lshlrev_b32_e32 v92, 16, v80
	v_and_b32_e32 v93, 0xffff0000, v80
	v_lshlrev_b32_e32 v94, 16, v81
	v_and_b32_e32 v95, 0xffff0000, v81
	v_pk_mul_f32 v[92:93], v[100:101], v[92:93] op_sel_hi:[0,1]
	v_pk_mul_f32 v[94:95], v[100:101], v[94:95] op_sel_hi:[0,1]
	v_pk_mul_f32 v[92:93], v[32:33], v[92:93]
	v_pk_mul_f32 v[94:95], v[34:35], v[94:95]
	global_store_dwordx4 v[108:109], v[92:95], off offset:-16 nt
	v_lshlrev_b32_e32 v96, 16, v82
	v_and_b32_e32 v97, 0xffff0000, v82
	v_lshlrev_b32_e32 v98, 16, v83
	v_and_b32_e32 v99, 0xffff0000, v83
	v_pk_mul_f32 v[96:97], v[100:101], v[96:97] op_sel_hi:[0,1]
	v_pk_mul_f32 v[98:99], v[100:101], v[98:99] op_sel_hi:[0,1]
	v_pk_mul_f32 v[96:97], v[36:37], v[96:97]
	v_pk_mul_f32 v[98:99], v[38:39], v[98:99]
	global_store_dwordx4 v[108:109], v[96:99], off nt
.Lfn_skipB:
	v_lshl_add_u64 v[6:7], v[108:109], 0, s[4:5]
	s_cmp_eq_u32 s14, 0
	s_cbranch_scc1 .Lfn_loop
